# INV GEMM EpiColT<16> epilogue rewritten: 64 per-token statistics loads rolled with 16 in flight (was 16 serialized load-wait chains), 32-bit store offsets
# baseline (speedup 1.0000x reference)
.LBB0_767:
	v_mov_b32_e32 v128, v206
	s_lshl_b32 s19, s47, 8
	s_add_i32 s19, s19, s41
	v_and_or_b32 v168, v128, 15, s19
	s_lshl_b32 s19, s46, 8
	v_lshrrev_b32_e32 v128, 1, v128
	v_and_or_b32 v128, v128, 24, s19
	v_or_b32_e32 v164, s42, v128
	v_mov_b32_e32 v175, v164
	v_mov_b32_e32 v217, v168
	v_lshlrev_b32_e32 v170, 6, v175
	v_add_u32_e32 v171, 0x2000, v170
	global_load_dwordx4 v[128:131], v170, s[4:5] offset:0
	global_load_dwordx4 v[132:135], v170, s[4:5] offset:16
	global_load_dwordx4 v[136:139], v170, s[4:5] offset:32
	global_load_dwordx4 v[140:143], v170, s[4:5] offset:48
	global_load_dwordx4 v[176:179], v170, s[4:5] offset:64
	global_load_dwordx4 v[180:183], v170, s[4:5] offset:80
	global_load_dwordx4 v[184:187], v170, s[4:5] offset:96
	global_load_dwordx4 v[188:191], v170, s[4:5] offset:112
	global_load_dwordx4 v[192:195], v170, s[4:5] offset:128
	global_load_dwordx4 v[196:199], v170, s[4:5] offset:144
	global_load_dwordx4 v[200:203], v170, s[4:5] offset:160
	global_load_dwordx4 v[218:221], v170, s[4:5] offset:176
	global_load_dwordx4 v[222:225], v170, s[4:5] offset:192
	global_load_dwordx4 v[226:229], v170, s[4:5] offset:208
	global_load_dwordx4 v[230:233], v170, s[4:5] offset:224
	global_load_dwordx4 v[150:153], v170, s[4:5] offset:240
	s_waitcnt vmcnt(12)
	v_add_f32_e32 v128, v128, v129
	v_add_f32_e32 v130, v130, v131
	v_add_f32_e32 v128, v128, v130
	v_add_f32_e32 v132, v132, v133
	v_add_f32_e32 v134, v134, v135
	v_add_f32_e32 v132, v132, v134
	v_add_f32_e32 v136, v136, v137
	v_add_f32_e32 v138, v138, v139
	v_add_f32_e32 v136, v136, v138
	v_add_f32_e32 v140, v140, v141
	v_add_f32_e32 v142, v142, v143
	v_add_f32_e32 v140, v140, v142
	v_add_f32_e32 v128, v128, v132
	v_add_f32_e32 v136, v136, v140
	v_add_f32_e32 v128, v128, v136
	v_fmamk_f32 v128, v128, 0x3a800000, v207
	v_rsq_f32_e32 v154, v128
	global_load_dwordx4 v[128:131], v170, s[4:5] offset:256
	global_load_dwordx4 v[132:135], v170, s[4:5] offset:272
	global_load_dwordx4 v[136:139], v170, s[4:5] offset:288
	global_load_dwordx4 v[140:143], v170, s[4:5] offset:304
	s_waitcnt vmcnt(12)
	v_add_f32_e32 v176, v176, v177
	v_add_f32_e32 v178, v178, v179
	v_add_f32_e32 v176, v176, v178
	v_add_f32_e32 v180, v180, v181
	v_add_f32_e32 v182, v182, v183
	v_add_f32_e32 v180, v180, v182
	v_add_f32_e32 v184, v184, v185
	v_add_f32_e32 v186, v186, v187
	v_add_f32_e32 v184, v184, v186
	v_add_f32_e32 v188, v188, v189
	v_add_f32_e32 v190, v190, v191
	v_add_f32_e32 v188, v188, v190
	v_add_f32_e32 v176, v176, v180
	v_add_f32_e32 v184, v184, v188
	v_add_f32_e32 v176, v176, v184
	v_fmamk_f32 v176, v176, 0x3a800000, v207
	v_rsq_f32_e32 v155, v176
	global_load_dwordx4 v[176:179], v170, s[4:5] offset:320
	global_load_dwordx4 v[180:183], v170, s[4:5] offset:336
	global_load_dwordx4 v[184:187], v170, s[4:5] offset:352
	global_load_dwordx4 v[188:191], v170, s[4:5] offset:368
	s_waitcnt vmcnt(12)
	v_add_f32_e32 v192, v192, v193
	v_add_f32_e32 v194, v194, v195
	v_add_f32_e32 v192, v192, v194
	v_add_f32_e32 v196, v196, v197
	v_add_f32_e32 v198, v198, v199
	v_add_f32_e32 v196, v196, v198
	v_add_f32_e32 v200, v200, v201
	v_add_f32_e32 v202, v202, v203
	v_add_f32_e32 v200, v200, v202
	v_add_f32_e32 v218, v218, v219
	v_add_f32_e32 v220, v220, v221
	v_add_f32_e32 v218, v218, v220
	v_add_f32_e32 v192, v192, v196
	v_add_f32_e32 v200, v200, v218
	v_add_f32_e32 v192, v192, v200
	v_fmamk_f32 v192, v192, 0x3a800000, v207
	v_rsq_f32_e32 v156, v192
	global_load_dwordx4 v[192:195], v170, s[4:5] offset:384
	global_load_dwordx4 v[196:199], v170, s[4:5] offset:400
	global_load_dwordx4 v[200:203], v170, s[4:5] offset:416
	global_load_dwordx4 v[218:221], v170, s[4:5] offset:432
	s_waitcnt vmcnt(12)
	v_add_f32_e32 v222, v222, v223
	v_add_f32_e32 v224, v224, v225
	v_add_f32_e32 v222, v222, v224
	v_add_f32_e32 v226, v226, v227
	v_add_f32_e32 v228, v228, v229
	v_add_f32_e32 v226, v226, v228
	v_add_f32_e32 v230, v230, v231
	v_add_f32_e32 v232, v232, v233
	v_add_f32_e32 v230, v230, v232
	v_add_f32_e32 v150, v150, v151
	v_add_f32_e32 v152, v152, v153
	v_add_f32_e32 v150, v150, v152
	v_add_f32_e32 v222, v222, v226
	v_add_f32_e32 v230, v230, v150
	v_add_f32_e32 v222, v222, v230
	v_fmamk_f32 v222, v222, 0x3a800000, v207
	v_rsq_f32_e32 v157, v222
	global_load_dwordx4 v[222:225], v170, s[4:5] offset:448
	global_load_dwordx4 v[226:229], v170, s[4:5] offset:464
	global_load_dwordx4 v[230:233], v170, s[4:5] offset:480
	global_load_dwordx4 v[150:153], v170, s[4:5] offset:496
	s_waitcnt vmcnt(12)
	v_add_f32_e32 v128, v128, v129
	v_add_f32_e32 v130, v130, v131
	v_add_f32_e32 v128, v128, v130
	v_add_f32_e32 v132, v132, v133
	v_add_f32_e32 v134, v134, v135
	v_add_f32_e32 v132, v132, v134
	v_add_f32_e32 v136, v136, v137
	v_add_f32_e32 v138, v138, v139
	v_add_f32_e32 v136, v136, v138
	v_add_f32_e32 v140, v140, v141
	v_add_f32_e32 v142, v142, v143
	v_add_f32_e32 v140, v140, v142
	v_add_f32_e32 v128, v128, v132
	v_add_f32_e32 v136, v136, v140
	v_add_f32_e32 v128, v128, v136
	v_fmamk_f32 v128, v128, 0x3a800000, v207
	v_rsq_f32_e32 v208, v128
	global_load_dwordx4 v[128:131], v171, s[4:5] offset:0
	global_load_dwordx4 v[132:135], v171, s[4:5] offset:16
	global_load_dwordx4 v[136:139], v171, s[4:5] offset:32
	global_load_dwordx4 v[140:143], v171, s[4:5] offset:48
	s_waitcnt vmcnt(12)
	v_add_f32_e32 v176, v176, v177
	v_add_f32_e32 v178, v178, v179
	v_add_f32_e32 v176, v176, v178
	v_add_f32_e32 v180, v180, v181
	v_add_f32_e32 v182, v182, v183
	v_add_f32_e32 v180, v180, v182
	v_add_f32_e32 v184, v184, v185
	v_add_f32_e32 v186, v186, v187
	v_add_f32_e32 v184, v184, v186
	v_add_f32_e32 v188, v188, v189
	v_add_f32_e32 v190, v190, v191
	v_add_f32_e32 v188, v188, v190
	v_add_f32_e32 v176, v176, v180
	v_add_f32_e32 v184, v184, v188
	v_add_f32_e32 v176, v176, v184
	v_fmamk_f32 v176, v176, 0x3a800000, v207
	v_rsq_f32_e32 v209, v176
	global_load_dwordx4 v[176:179], v171, s[4:5] offset:64
	global_load_dwordx4 v[180:183], v171, s[4:5] offset:80
	global_load_dwordx4 v[184:187], v171, s[4:5] offset:96
	global_load_dwordx4 v[188:191], v171, s[4:5] offset:112
	s_waitcnt vmcnt(12)
	v_add_f32_e32 v192, v192, v193
	v_add_f32_e32 v194, v194, v195
	v_add_f32_e32 v192, v192, v194
	v_add_f32_e32 v196, v196, v197
	v_add_f32_e32 v198, v198, v199
	v_add_f32_e32 v196, v196, v198
	v_add_f32_e32 v200, v200, v201
	v_add_f32_e32 v202, v202, v203
	v_add_f32_e32 v200, v200, v202
	v_add_f32_e32 v218, v218, v219
	v_add_f32_e32 v220, v220, v221
	v_add_f32_e32 v218, v218, v220
	v_add_f32_e32 v192, v192, v196
	v_add_f32_e32 v200, v200, v218
	v_add_f32_e32 v192, v192, v200
	v_fmamk_f32 v192, v192, 0x3a800000, v207
	v_rsq_f32_e32 v248, v192
	global_load_dwordx4 v[192:195], v171, s[4:5] offset:128
	global_load_dwordx4 v[196:199], v171, s[4:5] offset:144
	global_load_dwordx4 v[200:203], v171, s[4:5] offset:160
	global_load_dwordx4 v[218:221], v171, s[4:5] offset:176
	s_waitcnt vmcnt(12)
	v_add_f32_e32 v222, v222, v223
	v_add_f32_e32 v224, v224, v225
	v_add_f32_e32 v222, v222, v224
	v_add_f32_e32 v226, v226, v227
	v_add_f32_e32 v228, v228, v229
	v_add_f32_e32 v226, v226, v228
	v_add_f32_e32 v230, v230, v231
	v_add_f32_e32 v232, v232, v233
	v_add_f32_e32 v230, v230, v232
	v_add_f32_e32 v150, v150, v151
	v_add_f32_e32 v152, v152, v153
	v_add_f32_e32 v150, v150, v152
	v_add_f32_e32 v222, v222, v226
	v_add_f32_e32 v230, v230, v150
	v_add_f32_e32 v222, v222, v230
	v_fmamk_f32 v222, v222, 0x3a800000, v207
	v_rsq_f32_e32 v249, v222
	global_load_dwordx4 v[222:225], v171, s[4:5] offset:192
	global_load_dwordx4 v[226:229], v171, s[4:5] offset:208
	global_load_dwordx4 v[230:233], v171, s[4:5] offset:224
	global_load_dwordx4 v[150:153], v171, s[4:5] offset:240
	s_waitcnt vmcnt(12)
	v_add_f32_e32 v128, v128, v129
	v_add_f32_e32 v130, v130, v131
	v_add_f32_e32 v128, v128, v130
	v_add_f32_e32 v132, v132, v133
	v_add_f32_e32 v134, v134, v135
	v_add_f32_e32 v132, v132, v134
	v_add_f32_e32 v136, v136, v137
	v_add_f32_e32 v138, v138, v139
	v_add_f32_e32 v136, v136, v138
	v_add_f32_e32 v140, v140, v141
	v_add_f32_e32 v142, v142, v143
	v_add_f32_e32 v140, v140, v142
	v_add_f32_e32 v128, v128, v132
	v_add_f32_e32 v136, v136, v140
	v_add_f32_e32 v128, v128, v136
	v_fmamk_f32 v128, v128, 0x3a800000, v207
	v_rsq_f32_e32 v204, v128
	global_load_dwordx4 v[128:131], v171, s[4:5] offset:256
	global_load_dwordx4 v[132:135], v171, s[4:5] offset:272
	global_load_dwordx4 v[136:139], v171, s[4:5] offset:288
	global_load_dwordx4 v[140:143], v171, s[4:5] offset:304
	s_waitcnt vmcnt(12)
	v_add_f32_e32 v176, v176, v177
	v_add_f32_e32 v178, v178, v179
	v_add_f32_e32 v176, v176, v178
	v_add_f32_e32 v180, v180, v181
	v_add_f32_e32 v182, v182, v183
	v_add_f32_e32 v180, v180, v182
	v_add_f32_e32 v184, v184, v185
	v_add_f32_e32 v186, v186, v187
	v_add_f32_e32 v184, v184, v186
	v_add_f32_e32 v188, v188, v189
	v_add_f32_e32 v190, v190, v191
	v_add_f32_e32 v188, v188, v190
	v_add_f32_e32 v176, v176, v180
	v_add_f32_e32 v184, v184, v188
	v_add_f32_e32 v176, v176, v184
	v_fmamk_f32 v176, v176, 0x3a800000, v207
	v_rsq_f32_e32 v205, v176
	global_load_dwordx4 v[176:179], v171, s[4:5] offset:320
	global_load_dwordx4 v[180:183], v171, s[4:5] offset:336
	global_load_dwordx4 v[184:187], v171, s[4:5] offset:352
	global_load_dwordx4 v[188:191], v171, s[4:5] offset:368
	s_waitcnt vmcnt(12)
	v_add_f32_e32 v192, v192, v193
	v_add_f32_e32 v194, v194, v195
	v_add_f32_e32 v192, v192, v194
	v_add_f32_e32 v196, v196, v197
	v_add_f32_e32 v198, v198, v199
	v_add_f32_e32 v196, v196, v198
	v_add_f32_e32 v200, v200, v201
	v_add_f32_e32 v202, v202, v203
	v_add_f32_e32 v200, v200, v202
	v_add_f32_e32 v218, v218, v219
	v_add_f32_e32 v220, v220, v221
	v_add_f32_e32 v218, v218, v220
	v_add_f32_e32 v192, v192, v196
	v_add_f32_e32 v200, v200, v218
	v_add_f32_e32 v192, v192, v200
	v_fmamk_f32 v192, v192, 0x3a800000, v207
	v_rsq_f32_e32 v164, v192
	global_load_dwordx4 v[192:195], v171, s[4:5] offset:384
	global_load_dwordx4 v[196:199], v171, s[4:5] offset:400
	global_load_dwordx4 v[200:203], v171, s[4:5] offset:416
	global_load_dwordx4 v[218:221], v171, s[4:5] offset:432
	s_waitcnt vmcnt(12)
	v_add_f32_e32 v222, v222, v223
	v_add_f32_e32 v224, v224, v225
	v_add_f32_e32 v222, v222, v224
	v_add_f32_e32 v226, v226, v227
	v_add_f32_e32 v228, v228, v229
	v_add_f32_e32 v226, v226, v228
	v_add_f32_e32 v230, v230, v231
	v_add_f32_e32 v232, v232, v233
	v_add_f32_e32 v230, v230, v232
	v_add_f32_e32 v150, v150, v151
	v_add_f32_e32 v152, v152, v153
	v_add_f32_e32 v150, v150, v152
	v_add_f32_e32 v222, v222, v226
	v_add_f32_e32 v230, v230, v150
	v_add_f32_e32 v222, v222, v230
	v_fmamk_f32 v222, v222, 0x3a800000, v207
	v_rsq_f32_e32 v165, v222
	global_load_dwordx4 v[222:225], v171, s[4:5] offset:448
	global_load_dwordx4 v[226:229], v171, s[4:5] offset:464
	global_load_dwordx4 v[230:233], v171, s[4:5] offset:480
	global_load_dwordx4 v[150:153], v171, s[4:5] offset:496
	s_waitcnt vmcnt(12)
	v_add_f32_e32 v128, v128, v129
	v_add_f32_e32 v130, v130, v131
	v_add_f32_e32 v128, v128, v130
	v_add_f32_e32 v132, v132, v133
	v_add_f32_e32 v134, v134, v135
	v_add_f32_e32 v132, v132, v134
	v_add_f32_e32 v136, v136, v137
	v_add_f32_e32 v138, v138, v139
	v_add_f32_e32 v136, v136, v138
	v_add_f32_e32 v140, v140, v141
	v_add_f32_e32 v142, v142, v143
	v_add_f32_e32 v140, v140, v142
	v_add_f32_e32 v128, v128, v132
	v_add_f32_e32 v136, v136, v140
	v_add_f32_e32 v128, v128, v136
	v_fmamk_f32 v128, v128, 0x3a800000, v207
	v_rsq_f32_e32 v166, v128
	s_waitcnt vmcnt(8)
	v_add_f32_e32 v176, v176, v177
	v_add_f32_e32 v178, v178, v179
	v_add_f32_e32 v176, v176, v178
	v_add_f32_e32 v180, v180, v181
	v_add_f32_e32 v182, v182, v183
	v_add_f32_e32 v180, v180, v182
	v_add_f32_e32 v184, v184, v185
	v_add_f32_e32 v186, v186, v187
	v_add_f32_e32 v184, v184, v186
	v_add_f32_e32 v188, v188, v189
	v_add_f32_e32 v190, v190, v191
	v_add_f32_e32 v188, v188, v190
	v_add_f32_e32 v176, v176, v180
	v_add_f32_e32 v184, v184, v188
	v_add_f32_e32 v176, v176, v184
	v_fmamk_f32 v176, v176, 0x3a800000, v207
	v_rsq_f32_e32 v167, v176
	s_waitcnt vmcnt(4)
	v_add_f32_e32 v192, v192, v193
	v_add_f32_e32 v194, v194, v195
	v_add_f32_e32 v192, v192, v194
	v_add_f32_e32 v196, v196, v197
	v_add_f32_e32 v198, v198, v199
	v_add_f32_e32 v196, v196, v198
	v_add_f32_e32 v200, v200, v201
	v_add_f32_e32 v202, v202, v203
	v_add_f32_e32 v200, v200, v202
	v_add_f32_e32 v218, v218, v219
	v_add_f32_e32 v220, v220, v221
	v_add_f32_e32 v218, v218, v220
	v_add_f32_e32 v192, v192, v196
	v_add_f32_e32 v200, v200, v218
	v_add_f32_e32 v192, v192, v200
	v_fmamk_f32 v192, v192, 0x3a800000, v207
	v_rsq_f32_e32 v168, v192
	s_waitcnt vmcnt(0)
	v_add_f32_e32 v222, v222, v223
	v_add_f32_e32 v224, v224, v225
	v_add_f32_e32 v222, v222, v224
	v_add_f32_e32 v226, v226, v227
	v_add_f32_e32 v228, v228, v229
	v_add_f32_e32 v226, v226, v228
	v_add_f32_e32 v230, v230, v231
	v_add_f32_e32 v232, v232, v233
	v_add_f32_e32 v230, v230, v232
	v_add_f32_e32 v150, v150, v151
	v_add_f32_e32 v152, v152, v153
	v_add_f32_e32 v150, v150, v152
	v_add_f32_e32 v222, v222, v226
	v_add_f32_e32 v230, v230, v150
	v_add_f32_e32 v222, v222, v230
	v_fmamk_f32 v222, v222, 0x3a800000, v207
	v_rsq_f32_e32 v169, v222
	v_lshlrev_b32_e32 v128, 16, v217
	v_lshl_add_u32 v128, v175, 1, v128
	v_add_u32_e32 v129, 0x100000, v128
	v_add_u32_e32 v130, 0x200000, v128
	v_add_u32_e32 v131, 0x300000, v128
	v_add_u32_e32 v132, 0x800000, v128
	v_add_u32_e32 v133, 0x900000, v128
	v_add_u32_e32 v134, 0xa00000, v128
	v_add_u32_e32 v135, 0xb00000, v128
	v_pk_mul_f32 v[124:125], v[124:125], v[154:155]
	v_pk_mul_f32 v[126:127], v[126:127], v[156:157]
	v_cvt_pk_bf16_f32 v176, v124, v125
	v_cvt_pk_bf16_f32 v177, v126, v127
	global_store_dwordx2 v128, v[176:177], s[14:15]
	v_pk_mul_f32 v[120:121], v[120:121], v[154:155]
	v_pk_mul_f32 v[122:123], v[122:123], v[156:157]
	v_cvt_pk_bf16_f32 v178, v120, v121
	v_cvt_pk_bf16_f32 v179, v122, v123
	global_store_dwordx2 v129, v[178:179], s[14:15]
	v_pk_mul_f32 v[116:117], v[116:117], v[154:155]
	v_pk_mul_f32 v[118:119], v[118:119], v[156:157]
	v_cvt_pk_bf16_f32 v180, v116, v117
	v_cvt_pk_bf16_f32 v181, v118, v119
	global_store_dwordx2 v130, v[180:181], s[14:15]
	v_pk_mul_f32 v[112:113], v[112:113], v[154:155]
	v_pk_mul_f32 v[114:115], v[114:115], v[156:157]
	v_cvt_pk_bf16_f32 v182, v112, v113
	v_cvt_pk_bf16_f32 v183, v114, v115
	global_store_dwordx2 v131, v[182:183], s[14:15]
	v_pk_mul_f32 v[108:109], v[108:109], v[154:155]
	v_pk_mul_f32 v[110:111], v[110:111], v[156:157]
	v_cvt_pk_bf16_f32 v176, v108, v109
	v_cvt_pk_bf16_f32 v177, v110, v111
	global_store_dwordx2 v132, v[176:177], s[14:15]
	v_pk_mul_f32 v[104:105], v[104:105], v[154:155]
	v_pk_mul_f32 v[106:107], v[106:107], v[156:157]
	v_cvt_pk_bf16_f32 v178, v104, v105
	v_cvt_pk_bf16_f32 v179, v106, v107
	global_store_dwordx2 v133, v[178:179], s[14:15]
	v_pk_mul_f32 v[100:101], v[100:101], v[154:155]
	v_pk_mul_f32 v[102:103], v[102:103], v[156:157]
	v_cvt_pk_bf16_f32 v180, v100, v101
	v_cvt_pk_bf16_f32 v181, v102, v103
	global_store_dwordx2 v134, v[180:181], s[14:15]
	v_pk_mul_f32 v[96:97], v[96:97], v[154:155]
	v_pk_mul_f32 v[98:99], v[98:99], v[156:157]
	v_cvt_pk_bf16_f32 v182, v96, v97
	v_cvt_pk_bf16_f32 v183, v98, v99
	global_store_dwordx2 v135, v[182:183], s[14:15]
	v_pk_mul_f32 v[92:93], v[92:93], v[208:209]
	v_pk_mul_f32 v[94:95], v[94:95], v[248:249]
	v_cvt_pk_bf16_f32 v176, v92, v93
	v_cvt_pk_bf16_f32 v177, v94, v95
	global_store_dwordx2 v128, v[176:177], s[14:15] offset:8
	v_pk_mul_f32 v[88:89], v[88:89], v[208:209]
	v_pk_mul_f32 v[90:91], v[90:91], v[248:249]
	v_cvt_pk_bf16_f32 v178, v88, v89
	v_cvt_pk_bf16_f32 v179, v90, v91
	global_store_dwordx2 v129, v[178:179], s[14:15] offset:8
	v_pk_mul_f32 v[84:85], v[84:85], v[208:209]
	v_pk_mul_f32 v[86:87], v[86:87], v[248:249]
	v_cvt_pk_bf16_f32 v180, v84, v85
	v_cvt_pk_bf16_f32 v181, v86, v87
	global_store_dwordx2 v130, v[180:181], s[14:15] offset:8
	v_pk_mul_f32 v[80:81], v[80:81], v[208:209]
	v_pk_mul_f32 v[82:83], v[82:83], v[248:249]
	v_cvt_pk_bf16_f32 v182, v80, v81
	v_cvt_pk_bf16_f32 v183, v82, v83
	global_store_dwordx2 v131, v[182:183], s[14:15] offset:8
	v_pk_mul_f32 v[76:77], v[76:77], v[208:209]
	v_pk_mul_f32 v[78:79], v[78:79], v[248:249]
	v_cvt_pk_bf16_f32 v176, v76, v77
	v_cvt_pk_bf16_f32 v177, v78, v79
	global_store_dwordx2 v132, v[176:177], s[14:15] offset:8
	v_pk_mul_f32 v[72:73], v[72:73], v[208:209]
	v_pk_mul_f32 v[74:75], v[74:75], v[248:249]
	v_cvt_pk_bf16_f32 v178, v72, v73
	v_cvt_pk_bf16_f32 v179, v74, v75
	global_store_dwordx2 v133, v[178:179], s[14:15] offset:8
	v_pk_mul_f32 v[68:69], v[68:69], v[208:209]
	v_pk_mul_f32 v[70:71], v[70:71], v[248:249]
	v_cvt_pk_bf16_f32 v180, v68, v69
	v_cvt_pk_bf16_f32 v181, v70, v71
	global_store_dwordx2 v134, v[180:181], s[14:15] offset:8
	v_pk_mul_f32 v[64:65], v[64:65], v[208:209]
	v_pk_mul_f32 v[66:67], v[66:67], v[248:249]
	v_cvt_pk_bf16_f32 v182, v64, v65
	v_cvt_pk_bf16_f32 v183, v66, v67
	global_store_dwordx2 v135, v[182:183], s[14:15] offset:8
	v_pk_mul_f32 v[60:61], v[60:61], v[204:205]
	v_pk_mul_f32 v[62:63], v[62:63], v[164:165]
	v_cvt_pk_bf16_f32 v176, v60, v61
	v_cvt_pk_bf16_f32 v177, v62, v63
	global_store_dwordx2 v128, v[176:177], s[14:15] offset:256
	v_pk_mul_f32 v[56:57], v[56:57], v[204:205]
	v_pk_mul_f32 v[58:59], v[58:59], v[164:165]
	v_cvt_pk_bf16_f32 v178, v56, v57
	v_cvt_pk_bf16_f32 v179, v58, v59
	global_store_dwordx2 v129, v[178:179], s[14:15] offset:256
	v_pk_mul_f32 v[52:53], v[52:53], v[204:205]
	v_pk_mul_f32 v[54:55], v[54:55], v[164:165]
	v_cvt_pk_bf16_f32 v180, v52, v53
	v_cvt_pk_bf16_f32 v181, v54, v55
	global_store_dwordx2 v130, v[180:181], s[14:15] offset:256
	v_pk_mul_f32 v[48:49], v[48:49], v[204:205]
	v_pk_mul_f32 v[50:51], v[50:51], v[164:165]
	v_cvt_pk_bf16_f32 v182, v48, v49
	v_cvt_pk_bf16_f32 v183, v50, v51
	global_store_dwordx2 v131, v[182:183], s[14:15] offset:256
	v_pk_mul_f32 v[44:45], v[44:45], v[204:205]
	v_pk_mul_f32 v[46:47], v[46:47], v[164:165]
	v_cvt_pk_bf16_f32 v176, v44, v45
	v_cvt_pk_bf16_f32 v177, v46, v47
	global_store_dwordx2 v132, v[176:177], s[14:15] offset:256
	v_pk_mul_f32 v[40:41], v[40:41], v[204:205]
	v_pk_mul_f32 v[42:43], v[42:43], v[164:165]
	v_cvt_pk_bf16_f32 v178, v40, v41
	v_cvt_pk_bf16_f32 v179, v42, v43
	global_store_dwordx2 v133, v[178:179], s[14:15] offset:256
	v_pk_mul_f32 v[36:37], v[36:37], v[204:205]
	v_pk_mul_f32 v[38:39], v[38:39], v[164:165]
	v_cvt_pk_bf16_f32 v180, v36, v37
	v_cvt_pk_bf16_f32 v181, v38, v39
	global_store_dwordx2 v134, v[180:181], s[14:15] offset:256
	v_pk_mul_f32 v[32:33], v[32:33], v[204:205]
	v_pk_mul_f32 v[34:35], v[34:35], v[164:165]
	v_cvt_pk_bf16_f32 v182, v32, v33
	v_cvt_pk_bf16_f32 v183, v34, v35
	global_store_dwordx2 v135, v[182:183], s[14:15] offset:256
	v_pk_mul_f32 v[28:29], v[28:29], v[166:167]
	v_pk_mul_f32 v[30:31], v[30:31], v[168:169]
	v_cvt_pk_bf16_f32 v176, v28, v29
	v_cvt_pk_bf16_f32 v177, v30, v31
	global_store_dwordx2 v128, v[176:177], s[14:15] offset:264
	v_pk_mul_f32 v[24:25], v[24:25], v[166:167]
	v_pk_mul_f32 v[26:27], v[26:27], v[168:169]
	v_cvt_pk_bf16_f32 v178, v24, v25
	v_cvt_pk_bf16_f32 v179, v26, v27
	global_store_dwordx2 v129, v[178:179], s[14:15] offset:264
	v_pk_mul_f32 v[20:21], v[20:21], v[166:167]
	v_pk_mul_f32 v[22:23], v[22:23], v[168:169]
	v_cvt_pk_bf16_f32 v180, v20, v21
	v_cvt_pk_bf16_f32 v181, v22, v23
	global_store_dwordx2 v130, v[180:181], s[14:15] offset:264
	v_pk_mul_f32 v[16:17], v[16:17], v[166:167]
	v_pk_mul_f32 v[18:19], v[18:19], v[168:169]
	v_cvt_pk_bf16_f32 v182, v16, v17
	v_cvt_pk_bf16_f32 v183, v18, v19
	global_store_dwordx2 v131, v[182:183], s[14:15] offset:264
	v_pk_mul_f32 v[12:13], v[12:13], v[166:167]
	v_pk_mul_f32 v[14:15], v[14:15], v[168:169]
	v_cvt_pk_bf16_f32 v176, v12, v13
	v_cvt_pk_bf16_f32 v177, v14, v15
	global_store_dwordx2 v132, v[176:177], s[14:15] offset:264
	v_pk_mul_f32 v[8:9], v[8:9], v[166:167]
	v_pk_mul_f32 v[10:11], v[10:11], v[168:169]
	v_cvt_pk_bf16_f32 v178, v8, v9
	v_cvt_pk_bf16_f32 v179, v10, v11
	global_store_dwordx2 v133, v[178:179], s[14:15] offset:264
	v_pk_mul_f32 v[4:5], v[4:5], v[166:167]
	v_pk_mul_f32 v[6:7], v[6:7], v[168:169]
	v_cvt_pk_bf16_f32 v180, v4, v5
	v_cvt_pk_bf16_f32 v181, v6, v7
	global_store_dwordx2 v134, v[180:181], s[14:15] offset:264
	v_pk_mul_f32 v[0:1], v[0:1], v[166:167]
	v_pk_mul_f32 v[2:3], v[2:3], v[168:169]
	v_cvt_pk_bf16_f32 v182, v0, v1
	v_cvt_pk_bf16_f32 v183, v2, v3
	global_store_dwordx2 v135, v[182:183], s[14:15] offset:264
	s_mov_b32 s19, 0xb00000
	s_mov_b64 s[26:27], -1
	s_andn2_b64 vcc, exec, s[8:9]
	s_cbranch_vccnz .LBB0_756
	s_andn2_b64 vcc, exec, s[12:13]
	s_cbranch_vccnz .LBB0_755
	s_barrier
	s_branch .LBB0_755
